# code placement: heads of the GEMM K-loops (P1,P3,P5), the LRU tile loop and the attention tile loop aligned to 64 B
# speedup vs baseline: 1.0100x; 1.0100x over previous
.LBB0_143:
	s_ashr_i32 s49, s48, 31
	s_lshl_b64 s[14:15], s[48:49], 19
	s_add_u32 s50, s66, s14
	s_addc_u32 s51, s67, s15
	s_and_b64 s[14:15], s[6:7], exec
	s_cselect_b32 s11, s51, s9
	s_cselect_b32 s26, s50, s8
	s_ashr_i32 s47, s46, 31
	s_lshl_b64 s[14:15], s[46:47], 19
	s_add_u32 s58, s68, s14
	s_addc_u32 s59, s69, s15
	s_and_b64 s[14:15], s[6:7], exec
	s_cselect_b32 s47, s59, s13
	s_cselect_b32 s49, s58, s12
	s_add_u32 s8, s8, 0x40080
	s_addc_u32 s9, s9, 0
	s_add_u32 s60, s12, 0x100
	v_mov_b32_e32 v2, 0
	s_addc_u32 s61, s13, 0
	s_mov_b32 s62, -2
	v_mov_b32_e32 v3, v2
	v_mov_b32_e32 v4, v2
	v_mov_b32_e32 v5, v2
	v_mov_b32_e32 v6, v2
	v_mov_b32_e32 v7, v2
	v_mov_b32_e32 v8, v2
	v_mov_b32_e32 v9, v2
	v_mov_b32_e32 v18, v2
	v_mov_b32_e32 v19, v2
	v_mov_b32_e32 v20, v2
	v_mov_b32_e32 v21, v2
	v_mov_b32_e32 v22, v2
	v_mov_b32_e32 v23, v2
	v_mov_b32_e32 v24, v2
	v_mov_b32_e32 v25, v2
	v_mov_b32_e32 v34, v2
	v_mov_b32_e32 v35, v2
	v_mov_b32_e32 v36, v2
	v_mov_b32_e32 v37, v2
	v_mov_b32_e32 v38, v2
	v_mov_b32_e32 v39, v2
	v_mov_b32_e32 v40, v2
	v_mov_b32_e32 v41, v2
	v_mov_b32_e32 v50, v2
	v_mov_b32_e32 v51, v2
	v_mov_b32_e32 v52, v2
	v_mov_b32_e32 v53, v2
	v_mov_b32_e32 v54, v2
	v_mov_b32_e32 v55, v2
	v_mov_b32_e32 v56, v2
	v_mov_b32_e32 v57, v2
	v_mov_b32_e32 v10, v2
	v_mov_b32_e32 v11, v2
	v_mov_b32_e32 v12, v2
	v_mov_b32_e32 v13, v2
	v_mov_b32_e32 v14, v2
	v_mov_b32_e32 v15, v2
	v_mov_b32_e32 v16, v2
	v_mov_b32_e32 v17, v2
	v_mov_b32_e32 v26, v2
	v_mov_b32_e32 v27, v2
	v_mov_b32_e32 v28, v2
	v_mov_b32_e32 v29, v2
	v_mov_b32_e32 v30, v2
	v_mov_b32_e32 v31, v2
	v_mov_b32_e32 v32, v2
	v_mov_b32_e32 v33, v2
	v_mov_b32_e32 v42, v2
	v_mov_b32_e32 v43, v2
	v_mov_b32_e32 v44, v2
	v_mov_b32_e32 v45, v2
	v_mov_b32_e32 v46, v2
	v_mov_b32_e32 v47, v2
	v_mov_b32_e32 v48, v2
	v_mov_b32_e32 v49, v2
	v_mov_b32_e32 v58, v2
	v_mov_b32_e32 v59, v2
	v_mov_b32_e32 v60, v2
	v_mov_b32_e32 v61, v2
	v_mov_b32_e32 v62, v2
	v_mov_b32_e32 v63, v2
	v_mov_b32_e32 v64, v2
	v_mov_b32_e32 v65, v2
	v_mov_b32_e32 v66, v2
	v_mov_b32_e32 v67, v2
	v_mov_b32_e32 v68, v2
	v_mov_b32_e32 v69, v2
	v_mov_b32_e32 v70, v2
	v_mov_b32_e32 v71, v2
	v_mov_b32_e32 v72, v2
	v_mov_b32_e32 v73, v2
	v_mov_b32_e32 v82, v2
	v_mov_b32_e32 v83, v2
	v_mov_b32_e32 v84, v2
	v_mov_b32_e32 v85, v2
	v_mov_b32_e32 v86, v2
	v_mov_b32_e32 v87, v2
	v_mov_b32_e32 v88, v2
	v_mov_b32_e32 v89, v2
	v_mov_b32_e32 v98, v2
	v_mov_b32_e32 v99, v2
	v_mov_b32_e32 v100, v2
	v_mov_b32_e32 v101, v2
	v_mov_b32_e32 v102, v2
	v_mov_b32_e32 v103, v2
	v_mov_b32_e32 v104, v2
	v_mov_b32_e32 v105, v2
	v_mov_b32_e32 v114, v2
	v_mov_b32_e32 v115, v2
	v_mov_b32_e32 v116, v2
	v_mov_b32_e32 v117, v2
	v_mov_b32_e32 v118, v2
	v_mov_b32_e32 v119, v2
	v_mov_b32_e32 v120, v2
	v_mov_b32_e32 v121, v2
	v_mov_b32_e32 v74, v2
	v_mov_b32_e32 v75, v2
	v_mov_b32_e32 v76, v2
	v_mov_b32_e32 v77, v2
	v_mov_b32_e32 v78, v2
	v_mov_b32_e32 v79, v2
	v_mov_b32_e32 v80, v2
	v_mov_b32_e32 v81, v2
	v_mov_b32_e32 v90, v2
	v_mov_b32_e32 v91, v2
	v_mov_b32_e32 v92, v2
	v_mov_b32_e32 v93, v2
	v_mov_b32_e32 v94, v2
	v_mov_b32_e32 v95, v2
	v_mov_b32_e32 v96, v2
	v_mov_b32_e32 v97, v2
	v_mov_b32_e32 v106, v2
	v_mov_b32_e32 v107, v2
	v_mov_b32_e32 v108, v2
	v_mov_b32_e32 v109, v2
	v_mov_b32_e32 v110, v2
	v_mov_b32_e32 v111, v2
	v_mov_b32_e32 v112, v2
	v_mov_b32_e32 v113, v2
	v_mov_b32_e32 v122, v2
	v_mov_b32_e32 v123, v2
	v_mov_b32_e32 v124, v2
	v_mov_b32_e32 v125, v2
	v_mov_b32_e32 v126, v2
	v_mov_b32_e32 v127, v2
	v_mov_b32_e32 v128, v2
	v_mov_b32_e32 v129, v2
	.p2align	6

.LBB0_553:
	s_waitcnt vmcnt(0)
	s_mov_b64 s[14:15], 0
	.p2align	6

.LBB0_646:
	s_ashr_i32 s27, s26, 31
	v_cmp_lt_i64_e32 vcc, s[28:29], v[142:143]
	s_lshl_b64 s[28:29], s[26:27], 19
	s_add_u32 s28, s10, s28
	s_addc_u32 s29, s11, s29
	s_and_b64 s[30:31], vcc, exec
	s_cselect_b32 s27, s29, s41
	s_cselect_b32 s68, s28, s40
	s_ashr_i32 s25, s24, 31
	s_lshl_b64 s[30:31], s[24:25], 19
	s_add_u32 s30, s8, s30
	s_addc_u32 s31, s9, s31
	s_and_b64 s[42:43], vcc, exec
	s_cselect_b32 s25, s31, s39
	s_cselect_b32 s69, s30, s38
	s_add_u32 s72, s38, 0x100
	s_addc_u32 s73, s39, 0
	s_add_u32 s38, s40, 0x40080
	v_mov_b32_e32 v2, 0
	s_addc_u32 s39, s41, 0
	s_mov_b32 s74, -2
	v_mov_b32_e32 v3, v2
	v_mov_b32_e32 v4, v2
	v_mov_b32_e32 v5, v2
	v_mov_b32_e32 v6, v2
	v_mov_b32_e32 v7, v2
	v_mov_b32_e32 v8, v2
	v_mov_b32_e32 v9, v2
	v_mov_b32_e32 v10, v2
	v_mov_b32_e32 v11, v2
	v_mov_b32_e32 v12, v2
	v_mov_b32_e32 v13, v2
	v_mov_b32_e32 v18, v2
	v_mov_b32_e32 v19, v2
	v_mov_b32_e32 v20, v2
	v_mov_b32_e32 v21, v2
	v_mov_b32_e32 v26, v2
	v_mov_b32_e32 v27, v2
	v_mov_b32_e32 v28, v2
	v_mov_b32_e32 v29, v2
	v_mov_b32_e32 v34, v2
	v_mov_b32_e32 v35, v2
	v_mov_b32_e32 v36, v2
	v_mov_b32_e32 v37, v2
	v_mov_b32_e32 v42, v2
	v_mov_b32_e32 v43, v2
	v_mov_b32_e32 v44, v2
	v_mov_b32_e32 v45, v2
	v_mov_b32_e32 v50, v2
	v_mov_b32_e32 v51, v2
	v_mov_b32_e32 v52, v2
	v_mov_b32_e32 v53, v2
	v_mov_b32_e32 v14, v2
	v_mov_b32_e32 v15, v2
	v_mov_b32_e32 v16, v2
	v_mov_b32_e32 v17, v2
	v_mov_b32_e32 v22, v2
	v_mov_b32_e32 v23, v2
	v_mov_b32_e32 v24, v2
	v_mov_b32_e32 v25, v2
	v_mov_b32_e32 v30, v2
	v_mov_b32_e32 v31, v2
	v_mov_b32_e32 v32, v2
	v_mov_b32_e32 v33, v2
	v_mov_b32_e32 v38, v2
	v_mov_b32_e32 v39, v2
	v_mov_b32_e32 v40, v2
	v_mov_b32_e32 v41, v2
	v_mov_b32_e32 v46, v2
	v_mov_b32_e32 v47, v2
	v_mov_b32_e32 v48, v2
	v_mov_b32_e32 v49, v2
	v_mov_b32_e32 v54, v2
	v_mov_b32_e32 v55, v2
	v_mov_b32_e32 v56, v2
	v_mov_b32_e32 v57, v2
	v_mov_b32_e32 v58, v2
	v_mov_b32_e32 v59, v2
	v_mov_b32_e32 v60, v2
	v_mov_b32_e32 v61, v2
	v_mov_b32_e32 v62, v2
	v_mov_b32_e32 v63, v2
	v_mov_b32_e32 v64, v2
	v_mov_b32_e32 v65, v2
	v_mov_b32_e32 v66, v2
	v_mov_b32_e32 v67, v2
	v_mov_b32_e32 v68, v2
	v_mov_b32_e32 v69, v2
	v_mov_b32_e32 v70, v2
	v_mov_b32_e32 v71, v2
	v_mov_b32_e32 v72, v2
	v_mov_b32_e32 v73, v2
	v_mov_b32_e32 v74, v2
	v_mov_b32_e32 v75, v2
	v_mov_b32_e32 v76, v2
	v_mov_b32_e32 v77, v2
	v_mov_b32_e32 v82, v2
	v_mov_b32_e32 v83, v2
	v_mov_b32_e32 v84, v2
	v_mov_b32_e32 v85, v2
	v_mov_b32_e32 v90, v2
	v_mov_b32_e32 v91, v2
	v_mov_b32_e32 v92, v2
	v_mov_b32_e32 v93, v2
	v_mov_b32_e32 v98, v2
	v_mov_b32_e32 v99, v2
	v_mov_b32_e32 v100, v2
	v_mov_b32_e32 v101, v2
	v_mov_b32_e32 v106, v2
	v_mov_b32_e32 v107, v2
	v_mov_b32_e32 v108, v2
	v_mov_b32_e32 v109, v2
	v_mov_b32_e32 v114, v2
	v_mov_b32_e32 v115, v2
	v_mov_b32_e32 v116, v2
	v_mov_b32_e32 v117, v2
	v_mov_b32_e32 v78, v2
	v_mov_b32_e32 v79, v2
	v_mov_b32_e32 v80, v2
	v_mov_b32_e32 v81, v2
	v_mov_b32_e32 v86, v2
	v_mov_b32_e32 v87, v2
	v_mov_b32_e32 v88, v2
	v_mov_b32_e32 v89, v2
	v_mov_b32_e32 v94, v2
	v_mov_b32_e32 v95, v2
	v_mov_b32_e32 v96, v2
	v_mov_b32_e32 v97, v2
	v_mov_b32_e32 v102, v2
	v_mov_b32_e32 v103, v2
	v_mov_b32_e32 v104, v2
	v_mov_b32_e32 v105, v2
	v_mov_b32_e32 v110, v2
	v_mov_b32_e32 v111, v2
	v_mov_b32_e32 v112, v2
	v_mov_b32_e32 v113, v2
	v_mov_b32_e32 v118, v2
	v_mov_b32_e32 v119, v2
	v_mov_b32_e32 v120, v2
	v_mov_b32_e32 v121, v2
	v_mov_b32_e32 v122, v2
	v_mov_b32_e32 v123, v2
	v_mov_b32_e32 v124, v2
	v_mov_b32_e32 v125, v2
	v_mov_b32_e32 v126, v2
	v_mov_b32_e32 v127, v2
	v_mov_b32_e32 v128, v2
	v_mov_b32_e32 v129, v2
	.p2align	6

.LBB0_813:
	s_ashr_i32 s29, s28, 31
	v_cmp_lt_i64_e32 vcc, s[30:31], v[144:145]
	s_lshl_b64 s[30:31], s[28:29], 19
	s_add_u32 s30, s12, s30
	s_addc_u32 s31, s13, s31
	s_and_b64 s[36:37], vcc, exec
	s_cselect_b32 s7, s31, s41
	s_cselect_b32 s29, s30, s40
	s_ashr_i32 s27, s26, 31
	s_lshl_b64 s[36:37], s[26:27], 19
	s_add_u32 s36, s10, s36
	s_addc_u32 s37, s11, s37
	s_and_b64 s[44:45], vcc, exec
	s_cselect_b32 s27, s37, s43
	s_cselect_b32 s68, s36, s42
	s_add_u32 s40, s40, 0x40080
	s_addc_u32 s41, s41, 0
	s_add_u32 s69, s42, 0x100
	v_mov_b32_e32 v2, 0
	s_addc_u32 s72, s43, 0
	s_mov_b32 s73, -2
	v_mov_b32_e32 v3, v2
	v_mov_b32_e32 v4, v2
	v_mov_b32_e32 v5, v2
	v_mov_b32_e32 v6, v2
	v_mov_b32_e32 v7, v2
	v_mov_b32_e32 v8, v2
	v_mov_b32_e32 v9, v2
	v_mov_b32_e32 v18, v2
	v_mov_b32_e32 v19, v2
	v_mov_b32_e32 v20, v2
	v_mov_b32_e32 v21, v2
	v_mov_b32_e32 v22, v2
	v_mov_b32_e32 v23, v2
	v_mov_b32_e32 v24, v2
	v_mov_b32_e32 v25, v2
	v_mov_b32_e32 v34, v2
	v_mov_b32_e32 v35, v2
	v_mov_b32_e32 v36, v2
	v_mov_b32_e32 v37, v2
	v_mov_b32_e32 v38, v2
	v_mov_b32_e32 v39, v2
	v_mov_b32_e32 v40, v2
	v_mov_b32_e32 v41, v2
	v_mov_b32_e32 v50, v2
	v_mov_b32_e32 v51, v2
	v_mov_b32_e32 v52, v2
	v_mov_b32_e32 v53, v2
	v_mov_b32_e32 v54, v2
	v_mov_b32_e32 v55, v2
	v_mov_b32_e32 v56, v2
	v_mov_b32_e32 v57, v2
	v_mov_b32_e32 v10, v2
	v_mov_b32_e32 v11, v2
	v_mov_b32_e32 v12, v2
	v_mov_b32_e32 v13, v2
	v_mov_b32_e32 v14, v2
	v_mov_b32_e32 v15, v2
	v_mov_b32_e32 v16, v2
	v_mov_b32_e32 v17, v2
	v_mov_b32_e32 v26, v2
	v_mov_b32_e32 v27, v2
	v_mov_b32_e32 v28, v2
	v_mov_b32_e32 v29, v2
	v_mov_b32_e32 v30, v2
	v_mov_b32_e32 v31, v2
	v_mov_b32_e32 v32, v2
	v_mov_b32_e32 v33, v2
	v_mov_b32_e32 v42, v2
	v_mov_b32_e32 v43, v2
	v_mov_b32_e32 v44, v2
	v_mov_b32_e32 v45, v2
	v_mov_b32_e32 v46, v2
	v_mov_b32_e32 v47, v2
	v_mov_b32_e32 v48, v2
	v_mov_b32_e32 v49, v2
	v_mov_b32_e32 v58, v2
	v_mov_b32_e32 v59, v2
	v_mov_b32_e32 v60, v2
	v_mov_b32_e32 v61, v2
	v_mov_b32_e32 v62, v2
	v_mov_b32_e32 v63, v2
	v_mov_b32_e32 v64, v2
	v_mov_b32_e32 v65, v2
	v_mov_b32_e32 v66, v2
	v_mov_b32_e32 v67, v2
	v_mov_b32_e32 v68, v2
	v_mov_b32_e32 v69, v2
	v_mov_b32_e32 v70, v2
	v_mov_b32_e32 v71, v2
	v_mov_b32_e32 v72, v2
	v_mov_b32_e32 v73, v2
	v_mov_b32_e32 v82, v2
	v_mov_b32_e32 v83, v2
	v_mov_b32_e32 v84, v2
	v_mov_b32_e32 v85, v2
	v_mov_b32_e32 v86, v2
	v_mov_b32_e32 v87, v2
	v_mov_b32_e32 v88, v2
	v_mov_b32_e32 v89, v2
	v_mov_b32_e32 v98, v2
	v_mov_b32_e32 v99, v2
	v_mov_b32_e32 v100, v2
	v_mov_b32_e32 v101, v2
	v_mov_b32_e32 v102, v2
	v_mov_b32_e32 v103, v2
	v_mov_b32_e32 v104, v2
	v_mov_b32_e32 v105, v2
	v_mov_b32_e32 v114, v2
	v_mov_b32_e32 v115, v2
	v_mov_b32_e32 v116, v2
	v_mov_b32_e32 v117, v2
	v_mov_b32_e32 v118, v2
	v_mov_b32_e32 v119, v2
	v_mov_b32_e32 v120, v2
	v_mov_b32_e32 v121, v2
	v_mov_b32_e32 v74, v2
	v_mov_b32_e32 v75, v2
	v_mov_b32_e32 v76, v2
	v_mov_b32_e32 v77, v2
	v_mov_b32_e32 v78, v2
	v_mov_b32_e32 v79, v2
	v_mov_b32_e32 v80, v2
	v_mov_b32_e32 v81, v2
	v_mov_b32_e32 v90, v2
	v_mov_b32_e32 v91, v2
	v_mov_b32_e32 v92, v2
	v_mov_b32_e32 v93, v2
	v_mov_b32_e32 v94, v2
	v_mov_b32_e32 v95, v2
	v_mov_b32_e32 v96, v2
	v_mov_b32_e32 v97, v2
	v_mov_b32_e32 v106, v2
	v_mov_b32_e32 v107, v2
	v_mov_b32_e32 v108, v2
	v_mov_b32_e32 v109, v2
	v_mov_b32_e32 v110, v2
	v_mov_b32_e32 v111, v2
	v_mov_b32_e32 v112, v2
	v_mov_b32_e32 v113, v2
	v_mov_b32_e32 v122, v2
	v_mov_b32_e32 v123, v2
	v_mov_b32_e32 v124, v2
	v_mov_b32_e32 v125, v2
	v_mov_b32_e32 v126, v2
	v_mov_b32_e32 v127, v2
	v_mov_b32_e32 v128, v2
	v_mov_b32_e32 v129, v2
	.p2align	6

.LBB0_926:
	s_add_i32 s20, s25, 0x7f
	s_lshr_b32 s30, s20, 7
	s_and_b64 s[20:21], s[68:69], exec
	s_cselect_b32 s38, s76, 0x2984000
	s_ashr_i32 s29, s28, 31
	s_lshl_b64 s[26:27], s[26:27], 7
	s_lshl_b64 s[20:21], s[28:29], 12
	s_waitcnt vmcnt(12)
	v_mov_b32_e32 v67, v66
	v_mov_b32_e32 v68, v66
	v_mov_b32_e32 v69, v66
	s_waitcnt vmcnt(10)
	v_mov_b32_e32 v71, v70
	v_mov_b32_e32 v72, v70
	v_mov_b32_e32 v73, v70
	s_waitcnt vmcnt(8)
	v_mov_b32_e32 v75, v74
	v_mov_b32_e32 v76, v74
	v_mov_b32_e32 v77, v74
	s_waitcnt vmcnt(5)
	v_mov_b32_e32 v79, v78
	v_mov_b32_e32 v80, v78
	v_mov_b32_e32 v81, v78
	v_mov_b32_e32 v83, v82
	v_mov_b32_e32 v84, v82
	v_mov_b32_e32 v85, v82
	v_mov_b32_e32 v87, v86
	v_mov_b32_e32 v88, v86
	v_mov_b32_e32 v89, v86
	v_mov_b32_e32 v95, v94
	v_mov_b32_e32 v96, v94
	v_mov_b32_e32 v97, v94
	v_mov_b32_e32 v91, v90
	v_mov_b32_e32 v92, v90
	v_mov_b32_e32 v93, v90
	s_add_i32 s31, s25, -16
	v_lshl_add_u64 v[158:159], v[116:117], 0, s[26:27]
	s_lshl_b32 s38, s38, 2
	s_mov_b32 s39, s49
	s_mov_b32 s80, 0
	.p2align	6
